# v8 trimming plus MLA next-tile global loads issued after the first K-fragment LDS reads (LDS-latency shadow)
# speedup vs baseline: 1.0049x; 1.0049x over previous
; #define LAS __attribute__((address_space(3)))
; #define FA_SBAR() __builtin_amdgcn_sched_barrier(0)
; #define QK_MM(F0, F1, g) do { _Pragma("unroll") for (int e = 0; e < 2; ++e) { const int d0 = 2 * (g) + e; \
;         p0 = __builtin_amdgcn_mfma_f32_32x32x16_f16(F0[e], qr[d0], p0, 0, 0, 0); p1 = __builtin_amdgcn_mfma_f32_32x32x16_f16(F1[e], qr[d0], p1, 0, 0, 0); } } while (0)
; template <bool MLA>
; __device__ __forceinline__ void qkt2(f32x16& p0, f32x16& p1, const LAS char* lds, int kboff, int kroff, int r32, int hi, const half8* qr) {
;     const LAS char* kb[4];
; #pragma unroll
;     for (int dd = 0; dd < 4; ++dd) kb[dd] = lds + OFF_K + kboff + FA_KSWZ(r32, (dd * 16 + hi * 8) * 2);
;     constexpr int NG = MLA ? 6 : 4;
;     half8 fa0[2], fa1[2], fb0[2], fb1[2];
;     ...
; #pragma unroll
;     for (int r = 0; r < 16; ++r) { p0[r] = 0.f; p1[r] = 0.f; }
;     QK_LD(fa0, fa1, 0); FA_SBAR();
;     QK_LD(fb0, fb1, 1); FA_SBAR(); QK_MM(fa0, fa1, 0); FA_SBAR();
.LBB0_4974:
	s_and_b32 s8, s23, 1
	v_mov_b32_e32 v4, s8
	s_cmp_gt_i32 s22, s17
	s_cbranch_scc1 .Lmla_skipq
	v_lshlrev_b32_e32 v2, 14, v4
	v_add_u32_e32 v5, v209, v2
	v_add_u32_e32 v214, v5, v220
	v_add_u32_e32 v248, v5, v221
	ds_read_b128 v[6:9], v214 offset:32768
	ds_read_b128 v[10:13], v214 offset:40960
	ds_read_b128 v[14:17], v248 offset:32768
	ds_read_b128 v[230:233], v248 offset:40960
	v_add_u32_e32 v249, v5, v222
	v_add_u32_e32 v5, v5, v223
	ds_read_b128 v[234:237], v249 offset:32768
	ds_read_b128 v[240:243], v249 offset:40960
	ds_read_b128 v[244:247], v5 offset:32768
	ds_read_b128 v[194:197], v5 offset:40960
	s_and_b64 vcc, exec, s[6:7]
	s_cbranch_vccz .Lmla_q_nold
	v_add_u32_e32 v98, s22, v182
	v_add_u32_e32 v100, 64, v98
	v_ashrrev_i32_e32 v101, 31, v100
	v_add_u32_e32 v104, 0x60, v98
	v_lshlrev_b64 v[100:101], 8, v[100:101]
	v_ashrrev_i32_e32 v105, 31, v104
	v_lshl_add_u64 v[102:103], v[184:185], 0, v[100:101]
	v_lshlrev_b64 v[104:105], 8, v[104:105]
	v_lshl_add_u64 v[100:101], v[186:187], 0, v[100:101]
	v_lshl_add_u64 v[106:107], v[184:185], 0, v[104:105]
	global_load_dwordx4 v[114:117], v[102:103], off
	global_load_dwordx4 v[118:121], v[106:107], off
	v_lshl_add_u64 v[102:103], v[186:187], 0, v[104:105]
	global_load_dwordx4 v[122:125], v[100:101], off
	global_load_dwordx4 v[126:129], v[102:103], off
	v_add_u32_e32 v100, s22, v227
	v_ashrrev_i32_e32 v101, 31, v100
	v_lshlrev_b64 v[100:101], 7, v[100:101]
	v_lshl_add_u64 v[100:101], v[188:189], 0, v[100:101]
	global_load_dwordx4 v[178:181], v[100:101], off
; #define LAS __attribute__((address_space(3)))
; #define FA_SBAR() __builtin_amdgcn_sched_barrier(0)
; #define QK_MM(F0, F1, g) do { _Pragma("unroll") for (int e = 0; e < 2; ++e) { const int d0 = 2 * (g) + e; \
;         p0 = __builtin_amdgcn_mfma_f32_32x32x16_f16(F0[e], qr[d0], p0, 0, 0, 0); p1 = __builtin_amdgcn_mfma_f32_32x32x16_f16(F1[e], qr[d0], p1, 0, 0, 0); } } while (0)
; __device__ __forceinline__ void mask_tile(f32x16& p0, f32x16& p1, int dq, unsigned W) {
;     const float NEG = -__builtin_inff();
; #pragma unroll
;     for (int r = 0; r < 16; ++r) { const int c = (r & 3) + 8 * (r >> 2);
;         if ((unsigned)(dq - c) >= W) p0[r] = NEG;
;         if ((unsigned)(dq - c - 32) >= W) p1[r] = NEG; }
; }
; template <bool MLA>
; __device__ __forceinline__ void qkt2(f32x16& p0, f32x16& p1, const LAS char* lds, int kboff, int kroff, int r32, int hi, const half8* qr) {
;     const LAS char* kb[4];
; #pragma unroll
;     for (int dd = 0; dd < 4; ++dd) kb[dd] = lds + OFF_K + kboff + FA_KSWZ(r32, (dd * 16 + hi * 8) * 2);
;     constexpr int NG = MLA ? 6 : 4;
;     half8 fa0[2], fa1[2], fb0[2], fb1[2];
;     ...
; #pragma unroll
;     for (int r = 0; r < 16; ++r) { p0[r] = 0.f; p1[r] = 0.f; }
;     QK_LD(fa0, fa1, 0); FA_SBAR();
;     QK_LD(fb0, fb1, 1); FA_SBAR(); QK_MM(fa0, fa1, 0); FA_SBAR();
;     QK_LD(fa0, fa1, 2); FA_SBAR(); QK_MM(fb0, fb1, 1); FA_SBAR();
;     QK_LD(fb0, fb1, 3); FA_SBAR(); QK_MM(fa0, fa1, 2); FA_SBAR();
;     if constexpr (NG == 6) {
;         QK_LD(fa0, fa1, 4); FA_SBAR(); QK_MM(fb0, fb1, 3); FA_SBAR();
;         QK_LD(fb0, fb1, 5); FA_SBAR(); QK_MM(fa0, fa1, 4); FA_SBAR();
;         QK_MM(fb0, fb1, 5);
;     } else QK_MM(fb0, fb1, 3);
;     ...
; }
.Lmla_q_nold:
	s_waitcnt lgkmcnt(7)
	v_mfma_f32_32x32x16_f16 v[98:113], v[6:9], v[130:133], 0
	s_waitcnt lgkmcnt(6)
	v_mfma_f32_32x32x16_f16 v[82:97], v[10:13], v[130:133], 0
	s_waitcnt lgkmcnt(5)
	v_mfma_f32_32x32x16_f16 v[98:113], v[14:17], v[134:137], v[98:113]
	s_waitcnt lgkmcnt(4)
	v_mfma_f32_32x32x16_f16 v[82:97], v[230:233], v[134:137], v[82:97]
	ds_read_b128 v[6:9], v214 offset:32896
	ds_read_b128 v[10:13], v214 offset:41088
	ds_read_b128 v[14:17], v248 offset:32896
	ds_read_b128 v[230:233], v248 offset:41088
	s_waitcnt lgkmcnt(7)
	v_mfma_f32_32x32x16_f16 v[98:113], v[234:237], v[138:141], v[98:113]
	s_waitcnt lgkmcnt(6)
	v_mfma_f32_32x32x16_f16 v[82:97], v[240:243], v[138:141], v[82:97]
	s_waitcnt lgkmcnt(5)
	v_mfma_f32_32x32x16_f16 v[98:113], v[244:247], v[142:145], v[98:113]
	s_waitcnt lgkmcnt(4)
	v_mfma_f32_32x32x16_f16 v[82:97], v[194:197], v[142:145], v[82:97]
	ds_read_b128 v[194:197], v249 offset:32896
	ds_read_b128 v[234:237], v249 offset:41088
	ds_read_b128 v[240:243], v5 offset:32896
	ds_read_b128 v[244:247], v5 offset:41088
	s_waitcnt lgkmcnt(7)
	v_mfma_f32_32x32x16_f16 v[98:113], v[6:9], v[146:149], v[98:113]
	s_waitcnt lgkmcnt(6)
	v_mfma_f32_32x32x16_f16 v[82:97], v[10:13], v[146:149], v[82:97]
	s_waitcnt lgkmcnt(5)
	v_mfma_f32_32x32x16_f16 v[98:113], v[14:17], v[150:153], v[98:113]
	s_waitcnt lgkmcnt(4)
	v_mfma_f32_32x32x16_f16 v[82:97], v[230:233], v[150:153], v[82:97]
	v_lshl_add_u32 v16, v4, 13, v224
	v_add_u32_e32 v8, v16, v220
	v_add_u32_e32 v17, v16, v221
	ds_read_b128 v[4:7], v8
	ds_read_b128 v[8:11], v8 offset:4096
	ds_read_b128 v[12:15], v17
	ds_read_b128 v[230:233], v17 offset:4096
	s_waitcnt lgkmcnt(7)
	v_mfma_f32_32x32x16_f16 v[98:113], v[194:197], v[154:157], v[98:113]
	s_waitcnt lgkmcnt(6)
	v_mfma_f32_32x32x16_f16 v[82:97], v[234:237], v[154:157], v[82:97]
	s_waitcnt lgkmcnt(5)
	v_mfma_f32_32x32x16_f16 v[98:113], v[240:243], v[158:161], v[98:113]
	s_waitcnt lgkmcnt(4)
	v_mfma_f32_32x32x16_f16 v[82:97], v[244:247], v[158:161], v[82:97]
	v_add_u32_e32 v17, v16, v222
	v_add_u32_e32 v16, v16, v223
	ds_read_b128 v[194:197], v17
	ds_read_b128 v[234:237], v17 offset:4096
	ds_read_b128 v[240:243], v16
	ds_read_b128 v[244:247], v16 offset:4096
	s_waitcnt lgkmcnt(7)
	v_mfma_f32_32x32x16_f16 v[98:113], v[4:7], v[162:165], v[98:113]
	s_waitcnt lgkmcnt(6)
	v_mfma_f32_32x32x16_f16 v[82:97], v[8:11], v[162:165], v[82:97]
	s_waitcnt lgkmcnt(5)
	v_mfma_f32_32x32x16_f16 v[98:113], v[12:15], v[166:169], v[98:113]
	s_waitcnt lgkmcnt(4)
	v_mfma_f32_32x32x16_f16 v[82:97], v[230:233], v[166:169], v[82:97]
	s_waitcnt lgkmcnt(3)
	v_mfma_f32_32x32x16_f16 v[98:113], v[194:197], v[170:173], v[98:113]
	s_add_i32 s8, s22, 63
	s_cmp_le_i32 s8, s16
	s_waitcnt lgkmcnt(2)
	v_mfma_f32_32x32x16_f16 v[82:97], v[234:237], v[170:173], v[82:97]
	s_waitcnt lgkmcnt(1)
	v_mfma_f32_32x32x16_f16 v[98:113], v[240:243], v[174:177], v[98:113]
	s_waitcnt lgkmcnt(0)
	v_mfma_f32_32x32x16_f16 v[82:97], v[244:247], v[174:177], v[82:97]
	s_cbranch_scc1 .LBB0_4977
	v_add_u32_e32 v4, 59, v226
	v_cmp_gt_u32_e32 vcc, 2.0, v4
	v_add_u32_e32 v4, 27, v226
	s_nop 5
	v_cndmask_b32_e32 v98, v218, v98, vcc
	v_cmp_gt_u32_e32 vcc, 2.0, v4
	v_add_u32_e32 v4, 58, v226
	s_nop 0
	v_cndmask_b32_e32 v82, v218, v82, vcc
	v_cmp_gt_u32_e32 vcc, 2.0, v4
	v_add_u32_e32 v4, 26, v226
	s_nop 0
	v_cndmask_b32_e32 v99, v218, v99, vcc
	v_cmp_gt_u32_e32 vcc, 2.0, v4
	v_add_u32_e32 v4, 57, v226
	s_nop 0
	v_cndmask_b32_e32 v83, v218, v83, vcc
	v_cmp_gt_u32_e32 vcc, 2.0, v4
	v_add_u32_e32 v4, 25, v226
	s_nop 0
	v_cndmask_b32_e32 v100, v218, v100, vcc
	v_cmp_gt_u32_e32 vcc, 2.0, v4
	v_add_u32_e32 v4, 56, v226
	s_nop 0
	v_cndmask_b32_e32 v84, v218, v84, vcc
	v_cmp_gt_u32_e32 vcc, 2.0, v4
	v_add_u32_e32 v4, 24, v226
	s_nop 0
	v_cndmask_b32_e32 v101, v218, v101, vcc
	v_cmp_gt_u32_e32 vcc, 2.0, v4
	v_add_u32_e32 v4, 51, v226
	s_nop 0
	v_cndmask_b32_e32 v85, v218, v85, vcc
	v_cmp_gt_u32_e32 vcc, 2.0, v4
	v_add_u32_e32 v4, 19, v226
	s_nop 0
	v_cndmask_b32_e32 v102, v218, v102, vcc
	v_cmp_gt_u32_e32 vcc, 2.0, v4
	v_add_u32_e32 v4, 50, v226
	s_nop 0
	v_cndmask_b32_e32 v86, v218, v86, vcc
	v_cmp_gt_u32_e32 vcc, 2.0, v4
	v_add_u32_e32 v4, 18, v226
	s_nop 0
	v_cndmask_b32_e32 v103, v218, v103, vcc
	v_cmp_gt_u32_e32 vcc, 2.0, v4
	v_add_u32_e32 v4, 49, v226
	s_nop 0
	v_cndmask_b32_e32 v87, v218, v87, vcc
	v_cmp_gt_u32_e32 vcc, 2.0, v4
	v_add_u32_e32 v4, 17, v226
	s_nop 0
	v_cndmask_b32_e32 v104, v218, v104, vcc
	v_cmp_gt_u32_e32 vcc, 2.0, v4
	v_add_u32_e32 v4, 48, v226
	s_nop 0
	v_cndmask_b32_e32 v88, v218, v88, vcc
	v_cmp_gt_u32_e32 vcc, 2.0, v4
	v_add_u32_e32 v4, 16, v226
	s_nop 0
	v_cndmask_b32_e32 v105, v218, v105, vcc
	v_cmp_gt_u32_e32 vcc, 2.0, v4
	v_add_u32_e32 v4, 43, v226
	s_nop 0
	v_cndmask_b32_e32 v89, v218, v89, vcc
	v_cmp_gt_u32_e32 vcc, 2.0, v4
	v_add_u32_e32 v4, 11, v226
	s_nop 0
	v_cndmask_b32_e32 v106, v218, v106, vcc
	v_cmp_gt_u32_e32 vcc, 2.0, v4
	v_add_u32_e32 v4, 42, v226
	s_nop 0
	v_cndmask_b32_e32 v90, v218, v90, vcc
	v_cmp_gt_u32_e32 vcc, 2.0, v4
	v_add_u32_e32 v4, 10, v226
	s_nop 0
	v_cndmask_b32_e32 v107, v218, v107, vcc
	v_cmp_gt_u32_e32 vcc, 2.0, v4
	v_add_u32_e32 v4, 41, v226
	s_nop 0
	v_cndmask_b32_e32 v91, v218, v91, vcc
	v_cmp_gt_u32_e32 vcc, 2.0, v4
	v_add_u32_e32 v4, 9, v226
	s_nop 0
	v_cndmask_b32_e32 v108, v218, v108, vcc
	v_cmp_gt_u32_e32 vcc, 2.0, v4
	v_add_u32_e32 v4, 40, v226
	s_nop 0
	v_cndmask_b32_e32 v92, v218, v92, vcc
	v_cmp_gt_u32_e32 vcc, 2.0, v4
	v_add_u32_e32 v4, 8, v226
	s_nop 0
	v_cndmask_b32_e32 v109, v218, v109, vcc
	v_cmp_gt_u32_e32 vcc, 2.0, v4
	v_add_u32_e32 v4, 35, v226
	s_nop 0
	v_cndmask_b32_e32 v93, v218, v93, vcc
	v_cmp_gt_u32_e32 vcc, 2.0, v4
	v_add_u32_e32 v4, 3, v226
	s_nop 0
	v_cndmask_b32_e32 v110, v218, v110, vcc
	v_cmp_gt_u32_e32 vcc, 2.0, v4
	v_add_u32_e32 v4, 34, v226
	s_nop 0
	v_cndmask_b32_e32 v94, v218, v94, vcc
	v_cmp_gt_u32_e32 vcc, 2.0, v4
	v_add_u32_e32 v4, 2, v226
	s_nop 0
	v_cndmask_b32_e32 v111, v218, v111, vcc
	v_cmp_gt_u32_e32 vcc, 2.0, v4
	v_add_u32_e32 v4, 33, v226
	s_nop 0
	v_cndmask_b32_e32 v95, v218, v95, vcc
	v_cmp_gt_u32_e32 vcc, 2.0, v4
	v_add_u32_e32 v4, 1, v226
	s_nop 0
	v_cndmask_b32_e32 v112, v218, v112, vcc
	v_cmp_gt_u32_e32 vcc, 2.0, v4
	v_add_u32_e32 v4, 32, v226
	s_nop 0
	v_cndmask_b32_e32 v96, v218, v96, vcc
	v_cmp_gt_u32_e32 vcc, 2.0, v4
	s_nop 1
	v_cndmask_b32_e32 v113, v218, v113, vcc
	v_cmp_gt_u32_e32 vcc, 2.0, v226
	s_nop 1
	v_cndmask_b32_e32 v97, v218, v97, vcc

; template <int KIND>
; __device__ __forceinline__ void run_unit(LAS char* lds, const UnitArgs& U, int tid_in) {
;     ...
;     for (int t = 0; t < NT; ++t) {
;         if (t + 1 < NT) FA_LOADT(U.j_lo + t + 1);
.Lmla_skipq:
	s_and_b64 vcc, exec, s[6:7]
	s_cbranch_vccz .LBB0_4982
	v_add_u32_e32 v2, s22, v182
	v_add_u32_e32 v4, 64, v2
	v_ashrrev_i32_e32 v5, 31, v4
	v_add_u32_e32 v8, 0x60, v2
	v_lshlrev_b64 v[4:5], 8, v[4:5]
	v_ashrrev_i32_e32 v9, 31, v8
	v_lshl_add_u64 v[6:7], v[184:185], 0, v[4:5]
	v_lshlrev_b64 v[8:9], 8, v[8:9]
	v_lshl_add_u64 v[4:5], v[186:187], 0, v[4:5]
	v_lshl_add_u64 v[10:11], v[184:185], 0, v[8:9]
	global_load_dwordx4 v[114:117], v[6:7], off
	global_load_dwordx4 v[118:121], v[10:11], off
	v_lshl_add_u64 v[6:7], v[186:187], 0, v[8:9]
	global_load_dwordx4 v[122:125], v[4:5], off
	global_load_dwordx4 v[126:129], v[6:7], off
	v_add_u32_e32 v4, s22, v227
	v_ashrrev_i32_e32 v5, 31, v4
	v_lshlrev_b64 v[4:5], 7, v[4:5]
	v_lshl_add_u64 v[4:5], v[188:189], 0, v[4:5]
	global_load_dwordx4 v[178:181], v[4:5], off
	s_branch .LBB0_4982
